# CA-q projection (N=512): 256x128 half-tile units on all 256 workgroups instead of 128 full tiles; K loop rewritten for the half tile (2 MFMA blocks, 3 DMA stages per k-tile)
# speedup vs baseline: 1.0190x; 1.0021x over previous
; #define BID opqs((int)blockIdx.x)
; template <int E1, int E2>
; DI void gemm_phase2(const GemmP& g1, const GemmP& g2, char* smem) {
;   const int n1 = g1.Mt * g1.Nt, n2 = g2.Mt * g2.Nt;
;   for (int L = BID; L < n1 + n2; L += gridDim.x) {
;     int pm, pn;
;     if (L < n1) { unit_of(L, g1.Mt, g1.Nt, pm, pn); gemm_unit<E1>(g1, pm, pn); }
;     else { unit_of(L - n1, g2.Mt, g2.Nt, pm, pn); gemm_unit<E2>(g2, pm, pn); }
;   }
; DI void run_phase(const Params& p, int ph, char* smem) {
;     ...
;     case 7: {
;       GemmP g1 = mk_gemm(XB, DM, (const u16*)(ws + O_CAQ + L * SZ_CA), DM, DM, 64, 2);
;       g1.Cb = (u16*)(ws + O_CQ); g1.ldc = 512;
;       gemm_phase2<EPI_BF16, EPI_BF16>(g1, gz, smem);
;     } break;
.LBB0_213:
	s_andn2_b64 vcc, exec, s[6:7]
	s_cbranch_vccnz .LBB0_291
	v_readlane_b32 s22, v254, 0
	s_cmpk_gt_i32 s22, 0xff
	s_cbranch_scc1 .LBB0_291
	s_ashr_i32 s13, s12, 31
	s_lshl_b64 s[14:15], s[12:13], 21
	s_add_u32 s6, s90, s14
	s_addc_u32 s7, s91, s15
	s_add_u32 s13, s6, 0x7d00000
	s_addc_u32 s23, s7, 0
	s_add_u32 s16, s90, 0x3a480000
	s_addc_u32 s17, s91, 0
	s_branch .LBB0_217
.LBB0_216:
	s_or_b64 exec, exec, s[6:7]
	v_readlane_b32 s6, v254, 1
	s_add_i32 s22, s22, s6
	s_cmpk_gt_i32 s22, 0xff
	v_readlane_b32 s7, v254, 2
	s_cbranch_scc1 .LBB0_291

; #define TID opq((int)threadIdx.x)
; #define STAGE_A(P, br, kt) do { const u16* _g = Ab + (long)(br) * lda + (long)(kt) * 64; GLDS(_g + ao0, (char*)(P) + tid * 16); GLDS(_g + ao1, (char*)(P) + tid * 16 + 8192); } while (0)
; #define STAGE_B(P, br, kt) do { const u16* _g = Bb + (long)(br) * ldb + (long)(kt) * 64; GLDS(_g + bo0, (char*)(P) + tid * 16); GLDS(_g + bo1, (char*)(P) + tid * 16 + 8192); } while (0)
; #define WAIT_V(n) asm volatile("s_waitcnt vmcnt(" #n ")" ::: "memory")
; #define BAR __builtin_amdgcn_s_barrier()
; template <int EPI>
; DI void gemm_unit(const GemmP& g, int pm, int pn) {
;     ...
;   const int tid = TID;
;   const int wid = tid >> 6, lane = tid & 63, wr = wid >> 2, wc = wid & 3, fr = lane & 15, fq = lane >> 4;
;   const long lda = g.lda, ldb = g.ldb;
;   const u16* Ab = g.A; const u16* Bb = g.B;
;   const int brow = pm * 256, bcol = pn * 256;
;   int r0_, c0_, r1_, c1_; stage_rc(tid * 16, r0_, c0_); stage_rc(tid * 16 + 8192, r1_, c1_);
;   const long ao0 = (long)r0_ * lda + c0_, ao1 = (long)r1_ * lda + c1_, bo0 = (long)r0_ * ldb + c0_, bo1 = (long)r1_ * ldb + c1_;
;   f32x4 acc[2][2][4][2];
; #pragma unroll
;   for (int a = 0; a < 2; ++a)
; #pragma unroll
;     for (int b = 0; b < 2; ++b)
; #pragma unroll
;       for (int m = 0; m < 4; ++m)
; #pragma unroll
;         for (int n = 0; n < 2; ++n) acc[a][b][m][n] = (f32x4){0.f, 0.f, 0.f, 0.f};
;   bf16x8 At[4][2], B0[2][2], B1[2][2];
;   const int nt = g.K >> 6;
;   STAGE_B(SB(0, 0), bcol, 0); STAGE_A(SA(0, 0), brow, 0);
;   STAGE_B(SB(0, 1), bcol + 128, 0); STAGE_A(SA(0, 1), brow + 128, 0);
;   if (wr == 1) BAR;
;   WAIT_V(4); BAR;
;   STAGE_B(SB(1, 0), bcol, 1); STAGE_A(SA(1, 0), brow, 1); STAGE_B(SB(1, 1), bcol + 128, 1);
; DI bool unit_of(int L, int nM, int nN, int& pm, int& pn) {
;   const int nwg = nM * nN; if (L >= nwg) return false;
;   int wgid = L; { const int q = nwg / 8, r = nwg % 8, xcd = wgid % 8, off = wgid / 8; wgid = (xcd < r ? xcd * (q + 1) : r * (q + 1) + (xcd - r) * q) + off; }
;   const int nig = 8 * nN, gid = wgid / nig, fm = gid * 8, gsz = (nM - fm) < 8 ? (nM - fm) : 8;
;   pm = fm + ((wgid % nig) % gsz); pn = (wgid % nig) / gsz; return true;
; }
.LBB0_221:
	v_mov_b32_e32 v0, v201
	s_add_i32 s6, s9, s6
	s_waitcnt vmcnt(0)
	v_ashrrev_i32_e32 v2, 31, v0
	v_lshrrev_b32_e32 v2, 26, v2
	v_add_u32_e32 v2, v0, v2
	v_ashrrev_i32_e32 v3, 6, v2
	v_bfe_i32 v2, v0, 27, 1
	v_lshlrev_b32_e32 v22, 4, v0
	v_lshrrev_b32_e32 v2, 22, v2
	v_add_u32_e32 v2, v22, v2
	v_and_b32_e32 v2, 0xfffffc00, v2
	v_sub_u32_e32 v2, v22, v2
	v_lshrrev_b32_e32 v4, 4, v2
	v_bitop3_b32 v4, v4, v2, 32 bitop3:0x6c
	v_ashrrev_i32_e32 v2, 31, v2
	v_lshrrev_b32_e32 v2, 26, v2
	v_lshlrev_b32_e32 v5, 3, v3
	v_add_u32_e32 v2, v4, v2
	v_and_b32_e32 v5, -16, v5
	v_ashrrev_i32_e32 v6, 6, v2
	v_add_u32_e32 v2, v6, v5
	v_mul_i32_i24_e32 v5, 64, v6
	v_lshlrev_b32_e32 v3, 5, v3
	v_sub_u32_e32 v4, v4, v5
	v_and_b32_e32 v3, 32, v3
	v_ashrrev_i16_sdwa v4, v218, sext(v4) dst_sel:DWORD dst_unused:UNUSED_PAD src0_sel:DWORD src1_sel:BYTE_0
	v_add_u32_sdwa v4, v3, sext(v4) dst_sel:DWORD dst_unused:UNUSED_PAD src0_sel:DWORD src1_sel:WORD_0
	v_add_u32_e32 v3, 0x2000, v22
	s_ashr_i32 s7, s6, 31
	v_ashrrev_i32_e32 v5, 31, v3
	s_lshr_b32 s7, s7, 28
	v_lshrrev_b32_e32 v5, 22, v5
	s_add_i32 s7, s6, s7
	v_add_u32_e32 v5, v3, v5
	s_and_b32 s8, s7, 0xfff0
	v_ashrrev_i32_e32 v5, 10, v5
	s_sub_i32 s6, s6, s8
	v_mul_i32_i24_e32 v6, 0x400, v5
	s_bfe_i32 s8, s6, 0x80000
	v_sub_u32_e32 v3, v3, v6
	s_bfe_u32 s8, s8, 0x3000c
	v_lshrrev_b32_e32 v6, 4, v3
	s_add_i32 s8, s6, s8
	v_bitop3_b32 v3, v6, v3, 32 bitop3:0x6c
	s_bfe_i32 s9, s8, 0x80000
	s_and_b32 s8, s8, 0xf8
	v_ashrrev_i32_e32 v7, 31, v3
	s_sub_i32 s6, s6, s8
	v_lshrrev_b32_e32 v7, 26, v7
	s_sext_i32_i8 s6, s6
	s_lshl_b32 s7, s7, 7
	v_add_u32_e32 v7, v3, v7
	s_sext_i32_i16 s9, s9
	s_and_b32 s7, s7, 0xfffff800
	s_lshl_b32 s6, s6, 8
	v_ashrrev_i32_e32 v8, 6, v7
	v_and_b32_e32 v7, 0xc0, v7
	s_add_i32 s6, s6, s7
	v_lshlrev_b32_e32 v6, 3, v5
	v_lshlrev_b32_e32 v5, 5, v5
	v_sub_u32_e32 v3, v3, v7
	s_lshl_b32 s7, s9, 5
	v_and_b32_e32 v6, -16, v6
	v_and_b32_e32 v5, 32, v5
	v_ashrrev_i16_sdwa v3, v218, sext(v3) dst_sel:DWORD dst_unused:UNUSED_PAD src0_sel:DWORD src1_sel:BYTE_0
	s_and_b32 s8, s7, 0xffffff00
	s_and_b32 s6, s22, 7
	s_bfe_u32 s7, s22, 0x30003
	s_lshl_b32 s6, s6, 3
	s_add_i32 s6, s6, s7
	s_lshl_b32 s6, s6, 8
	s_lshr_b32 s8, s22, 6
	s_lshl_b32 s8, s8, 7
	v_add_u32_e32 v6, v8, v6
	v_add_u32_sdwa v8, v5, sext(v3) dst_sel:DWORD dst_unused:UNUSED_PAD src0_sel:DWORD src1_sel:WORD_0
	v_ashrrev_i32_e32 v3, 31, v2
	s_ashr_i32 s9, s8, 31
	v_ashrrev_i32_e32 v5, 31, v4
	v_lshlrev_b64 v[10:11], 11, v[2:3]
	s_lshl_b64 s[10:11], s[8:9], 12
	v_readlane_b32 s7, v254, 21
	v_ashrrev_i32_e32 v7, 31, v6
	v_lshl_add_u64 v[10:11], v[10:11], 0, v[4:5]
	s_add_u32 s18, s13, s10
	v_add_u32_e32 v150, s7, v22
	v_ashrrev_i32_e32 v9, 31, v8
	v_lshlrev_b64 v[12:13], 11, v[6:7]
	s_addc_u32 s19, s23, s11
	v_lshlrev_b64 v[24:25], 1, v[10:11]
	v_readfirstlane_b32 s7, v150
	v_add_u32_e32 v151, 0x2000, v150
	v_lshl_add_u64 v[12:13], v[12:13], 0, v[8:9]
	v_lshl_add_u64 v[10:11], s[18:19], 0, v[24:25]
	s_mov_b32 m0, s7
	v_readfirstlane_b32 s7, v151
	global_load_lds_dwordx4 v[10:11], off
	v_lshlrev_b64 v[26:27], 1, v[12:13]
	s_mov_b32 m0, s7
	s_ashr_i32 s7, s6, 31
	v_lshl_add_u64 v[12:13], s[18:19], 0, v[26:27]
	s_lshl_b64 s[18:19], s[6:7], 12
	s_add_u32 s20, s66, s18
	s_addc_u32 s21, s67, s19
	v_lshl_add_u64 v[14:15], s[20:21], 0, v[24:25]
	v_lshl_add_u64 v[16:17], s[20:21], 0, v[26:27]
	s_or_b32 s20, s8, 0x80
	s_ashr_i32 s21, s20, 31
	v_add_u32_e32 v153, 0, v22
	s_lshl_b64 s[20:21], s[20:21], 12
	v_readfirstlane_b32 s7, v153
	v_add_u32_e32 v154, 0x2000, v153
	s_add_u32 s20, s13, s20
	global_load_lds_dwordx4 v[12:13], off
	s_mov_b32 m0, s7
	v_readfirstlane_b32 s7, v154
	s_addc_u32 s21, s23, s21
	global_load_lds_dwordx4 v[14:15], off
	s_mov_b32 m0, s7
	v_lshl_add_u64 v[20:21], s[20:21], 0, v[24:25]
	v_readlane_b32 s7, v254, 22
	v_lshl_add_u64 v[18:19], s[20:21], 0, v[26:27]
	s_or_b32 s20, s6, 0x80
	v_add_u32_e32 v155, s7, v22
	s_ashr_i32 s21, s20, 31
	v_readfirstlane_b32 s7, v155
	v_add_u32_e32 v157, 0x2000, v155
	s_lshl_b64 s[20:21], s[20:21], 12
	global_load_lds_dwordx4 v[16:17], off
	s_mov_b32 m0, s7
	v_readfirstlane_b32 s7, v157
	s_add_u32 s20, s66, s20
	v_add_u32_e32 v158, 0x4000, v153
	s_mov_b32 m0, s7
	s_addc_u32 s21, s67, s21
	v_readfirstlane_b32 s7, v158
	v_add_u32_e32 v159, 0x6000, v153
	v_lshl_add_u64 v[130:131], s[20:21], 0, v[24:25]
	s_mov_b32 m0, s7
	v_readfirstlane_b32 s7, v159
	global_load_lds_dwordx4 v[130:131], off
	v_lshl_add_u64 v[132:133], s[20:21], 0, v[26:27]
	s_mov_b32 m0, s7
	v_ashrrev_i32_e32 v23, 8, v0
	global_load_lds_dwordx4 v[132:133], off
	v_cmp_eq_u32_e32 vcc, 1, v23
	s_and_saveexec_b64 s[20:21], vcc
	s_cbranch_execz .LBB0_223
	s_barrier
; #define STAGE_A(P, br, kt) do { const u16* _g = Ab + (long)(br) * lda + (long)(kt) * 64; GLDS(_g + ao0, (char*)(P) + tid * 16); GLDS(_g + ao1, (char*)(P) + tid * 16 + 8192); } while (0)
; #define STAGE_B(P, br, kt) do { const u16* _g = Bb + (long)(br) * ldb + (long)(kt) * 64; GLDS(_g + bo0, (char*)(P) + tid * 16); GLDS(_g + bo1, (char*)(P) + tid * 16 + 8192); } while (0)
; #define WAIT_V(n) asm volatile("s_waitcnt vmcnt(" #n ")" ::: "memory")
; #define BAR __builtin_amdgcn_s_barrier()
; template <int EPI>
; DI void gemm_unit(const GemmP& g, int pm, int pn) {
;     ...
;   int r0_, c0_, r1_, c1_; stage_rc(tid * 16, r0_, c0_); stage_rc(tid * 16 + 8192, r1_, c1_);
;   const long ao0 = (long)r0_ * lda + c0_, ao1 = (long)r1_ * lda + c1_, bo0 = (long)r0_ * ldb + c0_, bo1 = (long)r1_ * ldb + c1_;
;   f32x4 acc[2][2][4][2];
; #pragma unroll
;   for (int a = 0; a < 2; ++a)
; #pragma unroll
;     for (int b = 0; b < 2; ++b)
; #pragma unroll
;       for (int m = 0; m < 4; ++m)
; #pragma unroll
;         for (int n = 0; n < 2; ++n) acc[a][b][m][n] = (f32x4){0.f, 0.f, 0.f, 0.f};
;   bf16x8 At[4][2], B0[2][2], B1[2][2];
;   const int nt = g.K >> 6;
;   STAGE_B(SB(0, 0), bcol, 0); STAGE_A(SA(0, 0), brow, 0);
;   STAGE_B(SB(0, 1), bcol + 128, 0); STAGE_A(SA(0, 1), brow + 128, 0);
;   if (wr == 1) BAR;
;   WAIT_V(4); BAR;
;   STAGE_B(SB(1, 0), bcol, 1); STAGE_A(SA(1, 0), brow, 1); STAGE_B(SB(1, 1), bcol + 128, 1);
;   WAIT_V(6); BAR;
; #pragma unroll 1
;   for (int t = 0; t < nt - 2; t += 2) {
.LBB0_223:
	s_or_b64 exec, exec, s[20:21]
	v_readlane_b32 s9, v254, 23
	s_mov_b64 s[24:25], 0x80
	v_lshl_add_u64 v[10:11], v[10:11], 0, s[24:25]
	v_add_u32_e32 v160, s9, v22
	v_add_u32_e32 v161, 0x2000, v160
	v_readfirstlane_b32 s7, v160
	s_mov_b32 m0, s7
	v_readfirstlane_b32 s7, v161
	v_add_u32_e32 v162, 0x8000, v153
	s_waitcnt vmcnt(2)
	s_barrier
	global_load_lds_dwordx4 v[10:11], off
	v_lshl_add_u64 v[10:11], v[12:13], 0, s[24:25]
	s_mov_b32 m0, s7
	v_readfirstlane_b32 s7, v162
	v_add_u32_e32 v163, 0xa000, v153
	v_readlane_b32 s20, v254, 24
	global_load_lds_dwordx4 v[10:11], off
	v_lshl_add_u64 v[10:11], v[14:15], 0, s[24:25]
	s_mov_b32 m0, s7
	v_readfirstlane_b32 s7, v163
	v_add_u32_e32 v164, s20, v22
	global_load_lds_dwordx4 v[10:11], off
	v_lshl_add_u64 v[10:11], v[16:17], 0, s[24:25]
	s_mov_b32 m0, s7
	v_readfirstlane_b32 s7, v164
	v_add_u32_e32 v165, 0x2000, v164
	global_load_lds_dwordx4 v[10:11], off
	v_lshl_add_u64 v[10:11], v[20:21], 0, s[24:25]
	s_mov_b32 m0, s7
	v_readfirstlane_b32 s7, v165
	v_lshl_add_u64 v[10:11], v[18:19], 0, s[24:25]
	s_mov_b32 m0, s7
	v_and_b32_e32 v142, 15, v0
	v_bfe_u32 v144, v0, 4, 2
	v_lshlrev_b32_e32 v13, 2, v0
	v_lshlrev_b32_e32 v10, 4, v144
	v_lshlrev_b32_e32 v11, 6, v142
	v_and_b32_e32 v13, 32, v13
	v_bitop3_b32 v11, v10, v13, v11 bitop3:0x36
	v_readlane_b32 s7, v254, 21
	v_add_u32_e32 v16, s9, v11
	v_add_u32_e32 v17, s20, v11
	v_add_u32_e32 v14, s7, v11
	v_readlane_b32 s7, v254, 22
	v_add_u32_e32 v19, 0, v11
	s_add_u32 s10, s14, s10
	v_add_u32_e32 v15, s7, v11
	v_lshlrev_b32_e32 v11, 6, v0
	s_movk_i32 s7, 0x3c0
	v_and_or_b32 v10, v11, s7, v10
	s_addc_u32 s11, s15, s11
	v_lshlrev_b64 v[2:3], 12, v[2:3]
	v_xad_u32 v13, v10, v13, 0
	v_lshl_add_u64 v[10:11], s[10:11], 0, v[2:3]
	v_lshlrev_b64 v[4:5], 1, v[4:5]
	v_lshlrev_b64 v[6:7], 12, v[6:7]
	v_lshl_add_u64 v[2:3], s[18:19], 0, v[2:3]
	v_bfe_u32 v143, v0, 6, 2
	s_waitcnt vmcnt(4)
	v_lshlrev_b32_e32 v18, 13, v23
	v_lshlrev_b64 v[8:9], 1, v[8:9]
	v_lshl_add_u64 v[138:139], v[2:3], 0, v[4:5]
	v_lshl_add_u64 v[2:3], s[18:19], 0, v[6:7]
	v_lshlrev_b32_e32 v12, 12, v143
	v_or_b32_e32 v20, 0x800, v18
	v_or_b32_e32 v21, 0x1000, v18
	v_or_b32_e32 v22, 0x1800, v18
	v_lshl_add_u64 v[134:135], v[10:11], 0, v[4:5]
	v_lshl_add_u64 v[10:11], s[10:11], 0, v[6:7]
	v_lshl_add_u64 v[140:141], v[2:3], 0, v[8:9]
	v_mov_b32_e32 v2, 0
	v_lshlrev_b32_e32 v145, 6, v23
	v_lshl_add_u64 v[136:137], v[10:11], 0, v[8:9]
	s_mov_b32 s7, -2
	v_add_u32_e32 v167, v14, v12
	v_add_u32_e32 v149, v19, v18
	v_add_u32_e32 v148, v13, v20
	v_add_u32_e32 v147, v13, v21
	v_add_u32_e32 v146, v13, v22
	v_add_u32_e32 v166, v15, v12
	v_add_u32_e32 v156, v16, v12
	v_add_u32_e32 v152, v17, v12
	v_mov_b32_e32 v3, v2
	v_mov_b32_e32 v4, v2
	v_mov_b32_e32 v5, v2
	v_mov_b32_e32 v6, v2
	v_mov_b32_e32 v7, v2
	v_mov_b32_e32 v8, v2
	v_mov_b32_e32 v9, v2
	v_mov_b32_e32 v10, v2
	v_mov_b32_e32 v11, v2
	v_mov_b32_e32 v12, v2
	v_mov_b32_e32 v13, v2
	v_mov_b32_e32 v14, v2
	v_mov_b32_e32 v15, v2
	v_mov_b32_e32 v16, v2
	v_mov_b32_e32 v17, v2
	v_mov_b32_e32 v18, v2
	v_mov_b32_e32 v19, v2
	v_mov_b32_e32 v20, v2
	v_mov_b32_e32 v21, v2
	v_mov_b32_e32 v22, v2
	v_mov_b32_e32 v23, v2
	v_mov_b32_e32 v24, v2
	v_mov_b32_e32 v25, v2
	v_mov_b32_e32 v26, v2
	v_mov_b32_e32 v27, v2
	v_mov_b32_e32 v28, v2
	v_mov_b32_e32 v29, v2
	v_mov_b32_e32 v30, v2
	v_mov_b32_e32 v31, v2
	v_mov_b32_e32 v32, v2
	v_mov_b32_e32 v33, v2
	v_mov_b32_e32 v34, v2
	v_mov_b32_e32 v35, v2
	v_mov_b32_e32 v36, v2
	v_mov_b32_e32 v37, v2
	v_mov_b32_e32 v38, v2
	v_mov_b32_e32 v39, v2
	v_mov_b32_e32 v40, v2
	v_mov_b32_e32 v41, v2
	v_mov_b32_e32 v42, v2
	v_mov_b32_e32 v43, v2
	v_mov_b32_e32 v44, v2
	v_mov_b32_e32 v45, v2
	v_mov_b32_e32 v46, v2
	v_mov_b32_e32 v47, v2
	v_mov_b32_e32 v48, v2
	v_mov_b32_e32 v49, v2
	v_mov_b32_e32 v50, v2
	v_mov_b32_e32 v51, v2
	v_mov_b32_e32 v52, v2
	v_mov_b32_e32 v53, v2
	v_mov_b32_e32 v54, v2
	v_mov_b32_e32 v55, v2
	v_mov_b32_e32 v56, v2
	v_mov_b32_e32 v57, v2
	v_mov_b32_e32 v58, v2
	v_mov_b32_e32 v59, v2
	v_mov_b32_e32 v60, v2
	v_mov_b32_e32 v61, v2
	v_mov_b32_e32 v62, v2
	v_mov_b32_e32 v63, v2
	v_mov_b32_e32 v64, v2
	v_mov_b32_e32 v65, v2
	v_mov_b32_e32 v66, v2
	v_mov_b32_e32 v67, v2
	v_mov_b32_e32 v68, v2
	v_mov_b32_e32 v69, v2
	v_mov_b32_e32 v70, v2
	v_mov_b32_e32 v71, v2
	v_mov_b32_e32 v72, v2
	v_mov_b32_e32 v73, v2
	v_mov_b32_e32 v74, v2
	v_mov_b32_e32 v75, v2
	v_mov_b32_e32 v76, v2
	v_mov_b32_e32 v77, v2
	v_mov_b32_e32 v78, v2
	v_mov_b32_e32 v79, v2
	v_mov_b32_e32 v80, v2
	v_mov_b32_e32 v81, v2
	v_mov_b32_e32 v82, v2
	v_mov_b32_e32 v83, v2
	v_mov_b32_e32 v84, v2
	v_mov_b32_e32 v85, v2
	v_mov_b32_e32 v86, v2
	v_mov_b32_e32 v87, v2
	v_mov_b32_e32 v88, v2
	v_mov_b32_e32 v89, v2
	v_mov_b32_e32 v90, v2
	v_mov_b32_e32 v91, v2
	v_mov_b32_e32 v92, v2
	v_mov_b32_e32 v93, v2
	v_mov_b32_e32 v94, v2
	v_mov_b32_e32 v95, v2
	v_mov_b32_e32 v96, v2
	v_mov_b32_e32 v97, v2
	v_mov_b32_e32 v98, v2
	v_mov_b32_e32 v99, v2
	v_mov_b32_e32 v100, v2
	v_mov_b32_e32 v101, v2
	v_mov_b32_e32 v102, v2
	v_mov_b32_e32 v103, v2
	v_mov_b32_e32 v104, v2
	v_mov_b32_e32 v105, v2
	v_mov_b32_e32 v106, v2
	v_mov_b32_e32 v107, v2
	v_mov_b32_e32 v108, v2
	v_mov_b32_e32 v109, v2
	v_mov_b32_e32 v110, v2
	v_mov_b32_e32 v111, v2
	v_mov_b32_e32 v112, v2
	v_mov_b32_e32 v113, v2
	v_mov_b32_e32 v114, v2
	v_mov_b32_e32 v115, v2
	v_mov_b32_e32 v116, v2
	v_mov_b32_e32 v117, v2
	v_mov_b32_e32 v118, v2
	v_mov_b32_e32 v119, v2
	v_mov_b32_e32 v120, v2
	v_mov_b32_e32 v121, v2
	v_mov_b32_e32 v122, v2
	v_mov_b32_e32 v123, v2
	v_mov_b32_e32 v124, v2
	v_mov_b32_e32 v125, v2
	v_mov_b32_e32 v126, v2
	v_mov_b32_e32 v127, v2
	v_mov_b32_e32 v128, v2
	v_mov_b32_e32 v129, v2
	s_add_u32 s10, s90, 0x1a500100
	s_addc_u32 s11, s91, 0
	s_add_u32 s18, s90, 0x7d00100
	s_addc_u32 s19, s91, 0
	v_add_u32_e32 v234, 0x7ff80, v138
	v_add_u32_e32 v235, 0x7ff80, v140
	v_add_u32_e32 v236, 0x80000, v138
	v_add_u32_e32 v237, 0x80000, v140
	v_add_u32_e32 v238, 0x80, v138
	v_add_u32_e32 v239, 0x80, v140
	v_add_u32_e32 v240, 0x80, v134
	v_add_u32_e32 v241, 0x80, v136
	v_add_u32_e32 v168, 0xc000, v153
	v_add_u32_e32 v169, 0xe000, v153
	s_barrier
; #define STAGE_A(P, br, kt) do { const u16* _g = Ab + (long)(br) * lda + (long)(kt) * 64; GLDS(_g + ao0, (char*)(P) + tid * 16); GLDS(_g + ao1, (char*)(P) + tid * 16 + 8192); } while (0)
; #define STAGE_B(P, br, kt) do { const u16* _g = Bb + (long)(br) * ldb + (long)(kt) * 64; GLDS(_g + bo0, (char*)(P) + tid * 16); GLDS(_g + bo1, (char*)(P) + tid * 16 + 8192); } while (0)
; #define LDA(dst, b, h) _Pragma("unroll") for (int m = 0; m < 4; ++m) _Pragma("unroll") for (int k = 0; k < 2; ++k) \
;     dst[m][k] = *reinterpret_cast<const bf16x8*>((char*)SA(b, h) + lds_byte(wr * 64 + m * 16 + fr, k * 32 + fq * 8))
; #define LDB(dst, b, h) _Pragma("unroll") for (int n = 0; n < 2; ++n) _Pragma("unroll") for (int k = 0; k < 2; ++k) \
;     dst[n][k] = *reinterpret_cast<const bf16x8*>((char*)SB(b, h) + lds_byte(wc * 32 + n * 16 + fr, k * 32 + fq * 8))
; #define MMA(ai, bj, At_, Bt_) do { __builtin_amdgcn_s_setprio(1); \
;     _Pragma("unroll") for (int m = 0; m < 4; ++m) _Pragma("unroll") for (int n = 0; n < 2; ++n) _Pragma("unroll") for (int k = 0; k < 2; ++k) \
;       acc[ai][bj][m][n] = __builtin_amdgcn_mfma_f32_16x16x32_bf16(Bt_[n][k], At_[m][k], acc[ai][bj][m][n], 0, 0, 0); \
;     __builtin_amdgcn_s_setprio(0); } while (0)
; #define WAIT_V(n) asm volatile("s_waitcnt vmcnt(" #n ")" ::: "memory")
; #define WAIT_L(n) asm volatile("s_waitcnt lgkmcnt(" #n ")" ::: "memory")
; template <int EPI>
; DI void gemm_unit(const GemmP& g, int pm, int pn) {
;     ...
;   for (int t = 0; t < nt - 2; t += 2) {
;     LDB(B0, 0, 0); SCHED; LDA(At, 0, 0); STAGE_A(SA(1, 1), brow + 128, t + 1);
;     WAIT_L(8); BAR; WAIT_L(0); MMA(0, 0, At, B0); BAR; SCHED;
;     LDB(B1, 0, 1); STAGE_B(SB(0, 0), bcol, t + 2);
;     BAR; WAIT_L(0); MMA(0, 1, At, B1); BAR;
;     LDA(At, 0, 1); STAGE_A(SA(0, 0), brow, t + 2);
;     BAR; WAIT_L(0); MMA(1, 0, At, B0); BAR; SCHED;
;     STAGE_B(SB(0, 1), bcol + 128, t + 2);
;     WAIT_V(6); BAR; MMA(1, 1, At, B1); BAR;
;     LDB(B0, 1, 0); SCHED; LDA(At, 1, 0); STAGE_A(SA(0, 1), brow + 128, t + 2);
;     WAIT_L(8); BAR; WAIT_L(0); MMA(0, 0, At, B0); BAR; SCHED;
;     LDB(B1, 1, 1); STAGE_B(SB(1, 0), bcol, t + 3);
;     BAR; WAIT_L(0); MMA(0, 1, At, B1); BAR;
;     LDA(At, 1, 1); STAGE_A(SA(1, 0), brow, t + 3);
;     BAR; WAIT_L(0); MMA(1, 0, At, B0); BAR; SCHED;
;     STAGE_B(SB(1, 1), bcol + 128, t + 3);
;     WAIT_V(6); BAR; MMA(1, 1, At, B1); BAR;
;   }
.Lhq_loop:
	ds_read_b128 v[170:173], v167
	ds_read_b128 v[174:177], v167 offset:1024
	ds_read_b128 v[178:181], v167 offset:2048
	ds_read_b128 v[182:185], v167 offset:3072
	ds_read_b128 v[186:189], v149
	ds_read_b128 v[190:193], v149 offset:1024
	ds_read_b128 v[194:197], v148
	ds_read_b128 v[202:205], v148 offset:1024
	ds_read_b128 v[206:209], v147
	ds_read_b128 v[210:213], v147 offset:1024
	ds_read_b128 v[226:229], v146
	ds_read_b128 v[230:233], v146 offset:1024
	v_readfirstlane_b32 s9, v168
	s_nop 0
	s_mov_b32 m0, s9
	s_nop 0
	global_load_lds_dwordx4 v234, s[10:11]
	v_readfirstlane_b32 s9, v169
	s_nop 0
	s_mov_b32 m0, s9
	s_nop 0
	global_load_lds_dwordx4 v235, s[10:11]
	s_waitcnt vmcnt(6)
	s_waitcnt lgkmcnt(0)
	s_barrier
	s_setprio 1
	v_mfma_f32_16x16x32_bf16 v[126:129], v[170:173], v[186:189], v[126:129]
	v_mfma_f32_16x16x32_bf16 v[118:121], v[178:181], v[186:189], v[118:121]
	v_mfma_f32_16x16x32_bf16 v[110:113], v[170:173], v[194:197], v[110:113]
	v_mfma_f32_16x16x32_bf16 v[102:105], v[178:181], v[194:197], v[102:105]
	v_mfma_f32_16x16x32_bf16 v[94:97], v[170:173], v[206:209], v[94:97]
	v_mfma_f32_16x16x32_bf16 v[86:89], v[178:181], v[206:209], v[86:89]
	v_mfma_f32_16x16x32_bf16 v[78:81], v[170:173], v[226:229], v[78:81]
	v_mfma_f32_16x16x32_bf16 v[70:73], v[178:181], v[226:229], v[70:73]
	v_mfma_f32_16x16x32_bf16 v[126:129], v[174:177], v[190:193], v[126:129]
	v_mfma_f32_16x16x32_bf16 v[118:121], v[182:185], v[190:193], v[118:121]
	v_mfma_f32_16x16x32_bf16 v[110:113], v[174:177], v[202:205], v[110:113]
	v_mfma_f32_16x16x32_bf16 v[102:105], v[182:185], v[202:205], v[102:105]
	v_mfma_f32_16x16x32_bf16 v[94:97], v[174:177], v[210:213], v[94:97]
	v_mfma_f32_16x16x32_bf16 v[86:89], v[182:185], v[210:213], v[86:89]
	v_mfma_f32_16x16x32_bf16 v[78:81], v[174:177], v[230:233], v[78:81]
	v_mfma_f32_16x16x32_bf16 v[70:73], v[182:185], v[230:233], v[70:73]
	s_setprio 0
	s_barrier
	ds_read_b128 v[186:189], v149 offset:16384
	ds_read_b128 v[190:193], v149 offset:17408
	ds_read_b128 v[194:197], v148 offset:16384
	ds_read_b128 v[202:205], v148 offset:17408
	ds_read_b128 v[206:209], v147 offset:16384
	ds_read_b128 v[210:213], v147 offset:17408
	ds_read_b128 v[226:229], v146 offset:16384
	ds_read_b128 v[230:233], v146 offset:17408
	v_readfirstlane_b32 s9, v150
	s_nop 0
	s_mov_b32 m0, s9
	s_nop 0
	global_load_lds_dwordx4 v134, s[18:19]
	v_readfirstlane_b32 s9, v151
	s_nop 0
	s_mov_b32 m0, s9
	s_nop 0
	global_load_lds_dwordx4 v136, s[18:19]
	v_readfirstlane_b32 s9, v153
	s_nop 0
	s_mov_b32 m0, s9
	s_nop 0
	global_load_lds_dwordx4 v138, s[10:11]
	v_readfirstlane_b32 s9, v154
	s_nop 0
	s_mov_b32 m0, s9
	s_nop 0
	global_load_lds_dwordx4 v140, s[10:11]
	s_waitcnt vmcnt(6)
	s_waitcnt lgkmcnt(0)
	s_barrier
	s_setprio 1
	v_mfma_f32_16x16x32_bf16 v[62:65], v[170:173], v[186:189], v[62:65]
	v_mfma_f32_16x16x32_bf16 v[54:57], v[178:181], v[186:189], v[54:57]
	v_mfma_f32_16x16x32_bf16 v[46:49], v[170:173], v[194:197], v[46:49]
	v_mfma_f32_16x16x32_bf16 v[38:41], v[178:181], v[194:197], v[38:41]
	v_mfma_f32_16x16x32_bf16 v[30:33], v[170:173], v[206:209], v[30:33]
	v_mfma_f32_16x16x32_bf16 v[22:25], v[178:181], v[206:209], v[22:25]
	v_mfma_f32_16x16x32_bf16 v[14:17], v[170:173], v[226:229], v[14:17]
	v_mfma_f32_16x16x32_bf16 v[6:9], v[178:181], v[226:229], v[6:9]
	v_mfma_f32_16x16x32_bf16 v[62:65], v[174:177], v[190:193], v[62:65]
	v_mfma_f32_16x16x32_bf16 v[54:57], v[182:185], v[190:193], v[54:57]
	v_mfma_f32_16x16x32_bf16 v[46:49], v[174:177], v[202:205], v[46:49]
	v_mfma_f32_16x16x32_bf16 v[38:41], v[182:185], v[202:205], v[38:41]
	v_mfma_f32_16x16x32_bf16 v[30:33], v[174:177], v[210:213], v[30:33]
	v_mfma_f32_16x16x32_bf16 v[22:25], v[182:185], v[210:213], v[22:25]
	v_mfma_f32_16x16x32_bf16 v[14:17], v[174:177], v[230:233], v[14:17]
	v_mfma_f32_16x16x32_bf16 v[6:9], v[182:185], v[230:233], v[6:9]
	s_setprio 0
	s_barrier
	ds_read_b128 v[170:173], v156
	ds_read_b128 v[174:177], v156 offset:1024
	ds_read_b128 v[178:181], v156 offset:2048
	ds_read_b128 v[182:185], v156 offset:3072
	ds_read_b128 v[186:189], v149 offset:32768
	ds_read_b128 v[190:193], v149 offset:33792
	ds_read_b128 v[194:197], v148 offset:32768
	ds_read_b128 v[202:205], v148 offset:33792
	ds_read_b128 v[206:209], v147 offset:32768
	ds_read_b128 v[210:213], v147 offset:33792
	ds_read_b128 v[226:229], v146 offset:32768
	ds_read_b128 v[230:233], v146 offset:33792
	v_readfirstlane_b32 s9, v158
	s_nop 0
	s_mov_b32 m0, s9
	s_nop 0
	global_load_lds_dwordx4 v236, s[10:11]
	v_readfirstlane_b32 s9, v159
	s_nop 0
	s_mov_b32 m0, s9
	s_nop 0
	global_load_lds_dwordx4 v237, s[10:11]
	s_waitcnt vmcnt(6)
	s_waitcnt lgkmcnt(0)
	s_barrier
	s_setprio 1
	v_mfma_f32_16x16x32_bf16 v[126:129], v[170:173], v[186:189], v[126:129]
	v_mfma_f32_16x16x32_bf16 v[118:121], v[178:181], v[186:189], v[118:121]
	v_mfma_f32_16x16x32_bf16 v[110:113], v[170:173], v[194:197], v[110:113]
	v_mfma_f32_16x16x32_bf16 v[102:105], v[178:181], v[194:197], v[102:105]
	v_mfma_f32_16x16x32_bf16 v[94:97], v[170:173], v[206:209], v[94:97]
	v_mfma_f32_16x16x32_bf16 v[86:89], v[178:181], v[206:209], v[86:89]
	v_mfma_f32_16x16x32_bf16 v[78:81], v[170:173], v[226:229], v[78:81]
	v_mfma_f32_16x16x32_bf16 v[70:73], v[178:181], v[226:229], v[70:73]
	v_mfma_f32_16x16x32_bf16 v[126:129], v[174:177], v[190:193], v[126:129]
	v_mfma_f32_16x16x32_bf16 v[118:121], v[182:185], v[190:193], v[118:121]
	v_mfma_f32_16x16x32_bf16 v[110:113], v[174:177], v[202:205], v[110:113]
	v_mfma_f32_16x16x32_bf16 v[102:105], v[182:185], v[202:205], v[102:105]
	v_mfma_f32_16x16x32_bf16 v[94:97], v[174:177], v[210:213], v[94:97]
	v_mfma_f32_16x16x32_bf16 v[86:89], v[182:185], v[210:213], v[86:89]
	v_mfma_f32_16x16x32_bf16 v[78:81], v[174:177], v[230:233], v[78:81]
	v_mfma_f32_16x16x32_bf16 v[70:73], v[182:185], v[230:233], v[70:73]
	s_setprio 0
	s_barrier
; #define STAGE_A(P, br, kt) do { const u16* _g = Ab + (long)(br) * lda + (long)(kt) * 64; GLDS(_g + ao0, (char*)(P) + tid * 16); GLDS(_g + ao1, (char*)(P) + tid * 16 + 8192); } while (0)
; #define STAGE_B(P, br, kt) do { const u16* _g = Bb + (long)(br) * ldb + (long)(kt) * 64; GLDS(_g + bo0, (char*)(P) + tid * 16); GLDS(_g + bo1, (char*)(P) + tid * 16 + 8192); } while (0)
; #define LDA(dst, b, h) _Pragma("unroll") for (int m = 0; m < 4; ++m) _Pragma("unroll") for (int k = 0; k < 2; ++k) \
;     dst[m][k] = *reinterpret_cast<const bf16x8*>((char*)SA(b, h) + lds_byte(wr * 64 + m * 16 + fr, k * 32 + fq * 8))
; #define LDB(dst, b, h) _Pragma("unroll") for (int n = 0; n < 2; ++n) _Pragma("unroll") for (int k = 0; k < 2; ++k) \
;     dst[n][k] = *reinterpret_cast<const bf16x8*>((char*)SB(b, h) + lds_byte(wc * 32 + n * 16 + fr, k * 32 + fq * 8))
; #define MMA(ai, bj, At_, Bt_) do { __builtin_amdgcn_s_setprio(1); \
;     _Pragma("unroll") for (int m = 0; m < 4; ++m) _Pragma("unroll") for (int n = 0; n < 2; ++n) _Pragma("unroll") for (int k = 0; k < 2; ++k) \
;       acc[ai][bj][m][n] = __builtin_amdgcn_mfma_f32_16x16x32_bf16(Bt_[n][k], At_[m][k], acc[ai][bj][m][n], 0, 0, 0); \
;     __builtin_amdgcn_s_setprio(0); } while (0)
; #define WAIT_V(n) asm volatile("s_waitcnt vmcnt(" #n ")" ::: "memory")
; #define WAIT_L(n) asm volatile("s_waitcnt lgkmcnt(" #n ")" ::: "memory")
; #define BAR __builtin_amdgcn_s_barrier()
; #define SCHED __builtin_amdgcn_sched_barrier(0)
; template <int EPI>
; DI void gemm_unit(const GemmP& g, int pm, int pn) {
;     ...
;     WAIT_V(6); BAR; MMA(1, 1, At, B1); BAR;
;     LDB(B0, 1, 0); SCHED; LDA(At, 1, 0); STAGE_A(SA(0, 1), brow + 128, t + 2);
;     WAIT_L(8); BAR; WAIT_L(0); MMA(0, 0, At, B0); BAR; SCHED;
;     LDB(B1, 1, 1); STAGE_B(SB(1, 0), bcol, t + 3);
;     BAR; WAIT_L(0); MMA(0, 1, At, B1); BAR;
;     LDA(At, 1, 1); STAGE_A(SA(1, 0), brow, t + 3);
;     BAR; WAIT_L(0); MMA(1, 0, At, B0); BAR; SCHED;
;     STAGE_B(SB(1, 1), bcol + 128, t + 3);
;     WAIT_V(6); BAR; MMA(1, 1, At, B1); BAR;
;   }
;   { LDB(B0, 0, 0); LDA(At, 0, 0); STAGE_A(SA(1, 1), brow + 128, nt - 1);
;     BAR; WAIT_L(0); MMA(0, 0, At, B0); BAR;
;     LDB(B1, 0, 1); BAR; WAIT_L(0); MMA(0, 1, At, B1); BAR;
;     LDA(At, 0, 1); WAIT_V(4); BAR; WAIT_L(0); MMA(1, 0, At, B0); MMA(1, 1, At, B1); BAR; }
	ds_read_b128 v[186:189], v149 offset:49152
	ds_read_b128 v[190:193], v149 offset:50176
	ds_read_b128 v[194:197], v148 offset:49152
	ds_read_b128 v[202:205], v148 offset:50176
	ds_read_b128 v[206:209], v147 offset:49152
	ds_read_b128 v[210:213], v147 offset:50176
	ds_read_b128 v[226:229], v146 offset:49152
	ds_read_b128 v[230:233], v146 offset:50176
	v_readfirstlane_b32 s9, v160
	s_nop 0
	s_mov_b32 m0, s9
	s_nop 0
	global_load_lds_dwordx4 v240, s[18:19]
	v_readfirstlane_b32 s9, v161
	s_nop 0
	s_mov_b32 m0, s9
	s_nop 0
	global_load_lds_dwordx4 v241, s[18:19]
	v_readfirstlane_b32 s9, v162
	s_nop 0
	s_mov_b32 m0, s9
	s_nop 0
	global_load_lds_dwordx4 v238, s[10:11]
	v_readfirstlane_b32 s9, v163
	s_nop 0
	s_mov_b32 m0, s9
	s_nop 0
	global_load_lds_dwordx4 v239, s[10:11]
	s_waitcnt vmcnt(6)
	s_waitcnt lgkmcnt(0)
	s_barrier
	s_setprio 1
	v_mfma_f32_16x16x32_bf16 v[62:65], v[170:173], v[186:189], v[62:65]
	v_mfma_f32_16x16x32_bf16 v[54:57], v[178:181], v[186:189], v[54:57]
	v_mfma_f32_16x16x32_bf16 v[46:49], v[170:173], v[194:197], v[46:49]
	v_mfma_f32_16x16x32_bf16 v[38:41], v[178:181], v[194:197], v[38:41]
	v_mfma_f32_16x16x32_bf16 v[30:33], v[170:173], v[206:209], v[30:33]
	v_mfma_f32_16x16x32_bf16 v[22:25], v[178:181], v[206:209], v[22:25]
	v_mfma_f32_16x16x32_bf16 v[14:17], v[170:173], v[226:229], v[14:17]
	v_mfma_f32_16x16x32_bf16 v[6:9], v[178:181], v[226:229], v[6:9]
	v_mfma_f32_16x16x32_bf16 v[62:65], v[174:177], v[190:193], v[62:65]
	v_mfma_f32_16x16x32_bf16 v[54:57], v[182:185], v[190:193], v[54:57]
	v_mfma_f32_16x16x32_bf16 v[46:49], v[174:177], v[202:205], v[46:49]
	v_mfma_f32_16x16x32_bf16 v[38:41], v[182:185], v[202:205], v[38:41]
	v_mfma_f32_16x16x32_bf16 v[30:33], v[174:177], v[210:213], v[30:33]
	v_mfma_f32_16x16x32_bf16 v[22:25], v[182:185], v[210:213], v[22:25]
	v_mfma_f32_16x16x32_bf16 v[14:17], v[174:177], v[230:233], v[14:17]
	v_mfma_f32_16x16x32_bf16 v[6:9], v[182:185], v[230:233], v[6:9]
	s_setprio 0
	s_add_u32 s10, s10, 0x100
	s_addc_u32 s11, s11, 0
	s_add_u32 s18, s18, 0x100
	s_addc_u32 s19, s19, 0
	s_add_i32 s7, s7, 2
	s_cmp_lt_u32 s7, 28
	s_barrier
	s_cbranch_scc1 .Lhq_loop
	ds_read_b128 v[170:173], v167
	ds_read_b128 v[174:177], v167 offset:1024
	ds_read_b128 v[178:181], v167 offset:2048
	ds_read_b128 v[182:185], v167 offset:3072
	ds_read_b128 v[186:189], v149
	ds_read_b128 v[190:193], v149 offset:1024
	ds_read_b128 v[194:197], v148
	ds_read_b128 v[202:205], v148 offset:1024
	ds_read_b128 v[206:209], v147
	ds_read_b128 v[210:213], v147 offset:1024
	ds_read_b128 v[226:229], v146
	ds_read_b128 v[230:233], v146 offset:1024
	v_readfirstlane_b32 s9, v168
	s_nop 0
	s_mov_b32 m0, s9
	s_nop 0
	global_load_lds_dwordx4 v234, s[10:11]
	v_readfirstlane_b32 s9, v169
	s_nop 0
	s_mov_b32 m0, s9
	s_nop 0
	global_load_lds_dwordx4 v235, s[10:11]
	s_waitcnt vmcnt(6)
	s_waitcnt lgkmcnt(0)
	s_barrier
	s_setprio 1
	v_mfma_f32_16x16x32_bf16 v[126:129], v[170:173], v[186:189], v[126:129]
	v_mfma_f32_16x16x32_bf16 v[118:121], v[178:181], v[186:189], v[118:121]
	v_mfma_f32_16x16x32_bf16 v[110:113], v[170:173], v[194:197], v[110:113]
	v_mfma_f32_16x16x32_bf16 v[102:105], v[178:181], v[194:197], v[102:105]
	v_mfma_f32_16x16x32_bf16 v[94:97], v[170:173], v[206:209], v[94:97]
	v_mfma_f32_16x16x32_bf16 v[86:89], v[178:181], v[206:209], v[86:89]
	v_mfma_f32_16x16x32_bf16 v[78:81], v[170:173], v[226:229], v[78:81]
	v_mfma_f32_16x16x32_bf16 v[70:73], v[178:181], v[226:229], v[70:73]
	v_mfma_f32_16x16x32_bf16 v[126:129], v[174:177], v[190:193], v[126:129]
	v_mfma_f32_16x16x32_bf16 v[118:121], v[182:185], v[190:193], v[118:121]
	v_mfma_f32_16x16x32_bf16 v[110:113], v[174:177], v[202:205], v[110:113]
	v_mfma_f32_16x16x32_bf16 v[102:105], v[182:185], v[202:205], v[102:105]
	v_mfma_f32_16x16x32_bf16 v[94:97], v[174:177], v[210:213], v[94:97]
	v_mfma_f32_16x16x32_bf16 v[86:89], v[182:185], v[210:213], v[86:89]
	v_mfma_f32_16x16x32_bf16 v[78:81], v[174:177], v[230:233], v[78:81]
	v_mfma_f32_16x16x32_bf16 v[70:73], v[182:185], v[230:233], v[70:73]
	s_setprio 0
	s_barrier
	ds_read_b128 v[186:189], v149 offset:16384
	ds_read_b128 v[190:193], v149 offset:17408
	ds_read_b128 v[194:197], v148 offset:16384
	ds_read_b128 v[202:205], v148 offset:17408
	ds_read_b128 v[206:209], v147 offset:16384
	ds_read_b128 v[210:213], v147 offset:17408
	ds_read_b128 v[226:229], v146 offset:16384
	ds_read_b128 v[230:233], v146 offset:17408
	s_waitcnt vmcnt(2)
	s_waitcnt lgkmcnt(0)
	s_barrier
; #define STAGE_A(P, br, kt) do { const u16* _g = Ab + (long)(br) * lda + (long)(kt) * 64; GLDS(_g + ao0, (char*)(P) + tid * 16); GLDS(_g + ao1, (char*)(P) + tid * 16 + 8192); } while (0)
; #define LDA(dst, b, h) _Pragma("unroll") for (int m = 0; m < 4; ++m) _Pragma("unroll") for (int k = 0; k < 2; ++k) \
;     dst[m][k] = *reinterpret_cast<const bf16x8*>((char*)SA(b, h) + lds_byte(wr * 64 + m * 16 + fr, k * 32 + fq * 8))
; #define LDB(dst, b, h) _Pragma("unroll") for (int n = 0; n < 2; ++n) _Pragma("unroll") for (int k = 0; k < 2; ++k) \
;     dst[n][k] = *reinterpret_cast<const bf16x8*>((char*)SB(b, h) + lds_byte(wc * 32 + n * 16 + fr, k * 32 + fq * 8))
; #define MMA(ai, bj, At_, Bt_) do { __builtin_amdgcn_s_setprio(1); \
;     _Pragma("unroll") for (int m = 0; m < 4; ++m) _Pragma("unroll") for (int n = 0; n < 2; ++n) _Pragma("unroll") for (int k = 0; k < 2; ++k) \
;       acc[ai][bj][m][n] = __builtin_amdgcn_mfma_f32_16x16x32_bf16(Bt_[n][k], At_[m][k], acc[ai][bj][m][n], 0, 0, 0); \
;     __builtin_amdgcn_s_setprio(0); } while (0)
; #define WAIT_V(n) asm volatile("s_waitcnt vmcnt(" #n ")" ::: "memory")
; #define WAIT_L(n) asm volatile("s_waitcnt lgkmcnt(" #n ")" ::: "memory")
; #define BAR __builtin_amdgcn_s_barrier()
; template <int EPI>
; DI void gemm_unit(const GemmP& g, int pm, int pn) {
;     ...
;   { LDB(B0, 0, 0); LDA(At, 0, 0); STAGE_A(SA(1, 1), brow + 128, nt - 1);
;     BAR; WAIT_L(0); MMA(0, 0, At, B0); BAR;
;     LDB(B1, 0, 1); BAR; WAIT_L(0); MMA(0, 1, At, B1); BAR;
;     LDA(At, 0, 1); WAIT_V(4); BAR; WAIT_L(0); MMA(1, 0, At, B0); MMA(1, 1, At, B1); BAR; }
;   { LDB(B0, 1, 0); LDA(At, 1, 0); WAIT_V(2); BAR; WAIT_L(0); MMA(0, 0, At, B0); BAR;
;     LDB(B1, 1, 1); WAIT_V(0); BAR; WAIT_L(0); MMA(0, 1, At, B1); BAR;
;     LDA(At, 1, 1); BAR; WAIT_L(0); MMA(1, 0, At, B0); MMA(1, 1, At, B1); BAR; }
;   if (wr == 0) BAR;
	s_setprio 1
	v_mfma_f32_16x16x32_bf16 v[62:65], v[170:173], v[186:189], v[62:65]
	v_mfma_f32_16x16x32_bf16 v[54:57], v[178:181], v[186:189], v[54:57]
	v_mfma_f32_16x16x32_bf16 v[46:49], v[170:173], v[194:197], v[46:49]
	v_mfma_f32_16x16x32_bf16 v[38:41], v[178:181], v[194:197], v[38:41]
	v_mfma_f32_16x16x32_bf16 v[30:33], v[170:173], v[206:209], v[30:33]
	v_mfma_f32_16x16x32_bf16 v[22:25], v[178:181], v[206:209], v[22:25]
	v_mfma_f32_16x16x32_bf16 v[14:17], v[170:173], v[226:229], v[14:17]
	v_mfma_f32_16x16x32_bf16 v[6:9], v[178:181], v[226:229], v[6:9]
	v_mfma_f32_16x16x32_bf16 v[62:65], v[174:177], v[190:193], v[62:65]
	v_mfma_f32_16x16x32_bf16 v[54:57], v[182:185], v[190:193], v[54:57]
	v_mfma_f32_16x16x32_bf16 v[46:49], v[174:177], v[202:205], v[46:49]
	v_mfma_f32_16x16x32_bf16 v[38:41], v[182:185], v[202:205], v[38:41]
	v_mfma_f32_16x16x32_bf16 v[30:33], v[174:177], v[210:213], v[30:33]
	v_mfma_f32_16x16x32_bf16 v[22:25], v[182:185], v[210:213], v[22:25]
	v_mfma_f32_16x16x32_bf16 v[14:17], v[174:177], v[230:233], v[14:17]
	v_mfma_f32_16x16x32_bf16 v[6:9], v[182:185], v[230:233], v[6:9]
	s_setprio 0
	s_barrier
	ds_read_b128 v[170:173], v156
	ds_read_b128 v[174:177], v156 offset:1024
	ds_read_b128 v[178:181], v156 offset:2048
	ds_read_b128 v[182:185], v156 offset:3072
	ds_read_b128 v[186:189], v149 offset:32768
	ds_read_b128 v[190:193], v149 offset:33792
	ds_read_b128 v[194:197], v148 offset:32768
	ds_read_b128 v[202:205], v148 offset:33792
	ds_read_b128 v[206:209], v147 offset:32768
	ds_read_b128 v[210:213], v147 offset:33792
	ds_read_b128 v[226:229], v146 offset:32768
	ds_read_b128 v[230:233], v146 offset:33792
	s_waitcnt vmcnt(0)
	s_waitcnt lgkmcnt(0)
	s_barrier
	s_setprio 1
	v_mfma_f32_16x16x32_bf16 v[126:129], v[170:173], v[186:189], v[126:129]
	v_mfma_f32_16x16x32_bf16 v[118:121], v[178:181], v[186:189], v[118:121]
	v_mfma_f32_16x16x32_bf16 v[110:113], v[170:173], v[194:197], v[110:113]
	v_mfma_f32_16x16x32_bf16 v[102:105], v[178:181], v[194:197], v[102:105]
	v_mfma_f32_16x16x32_bf16 v[94:97], v[170:173], v[206:209], v[94:97]
	v_mfma_f32_16x16x32_bf16 v[86:89], v[178:181], v[206:209], v[86:89]
	v_mfma_f32_16x16x32_bf16 v[78:81], v[170:173], v[226:229], v[78:81]
	v_mfma_f32_16x16x32_bf16 v[70:73], v[178:181], v[226:229], v[70:73]
	v_mfma_f32_16x16x32_bf16 v[126:129], v[174:177], v[190:193], v[126:129]
	v_mfma_f32_16x16x32_bf16 v[118:121], v[182:185], v[190:193], v[118:121]
	v_mfma_f32_16x16x32_bf16 v[110:113], v[174:177], v[202:205], v[110:113]
	v_mfma_f32_16x16x32_bf16 v[102:105], v[182:185], v[202:205], v[102:105]
	v_mfma_f32_16x16x32_bf16 v[94:97], v[174:177], v[210:213], v[94:97]
	v_mfma_f32_16x16x32_bf16 v[86:89], v[182:185], v[210:213], v[86:89]
	v_mfma_f32_16x16x32_bf16 v[78:81], v[174:177], v[230:233], v[78:81]
	v_mfma_f32_16x16x32_bf16 v[70:73], v[182:185], v[230:233], v[70:73]
	s_setprio 0
	s_barrier
	ds_read_b128 v[186:189], v149 offset:49152
	ds_read_b128 v[190:193], v149 offset:50176
	ds_read_b128 v[194:197], v148 offset:49152
	ds_read_b128 v[202:205], v148 offset:50176
	ds_read_b128 v[206:209], v147 offset:49152
	ds_read_b128 v[210:213], v147 offset:50176
	ds_read_b128 v[226:229], v146 offset:49152
	ds_read_b128 v[230:233], v146 offset:50176
	s_waitcnt lgkmcnt(0)
	s_barrier
	s_setprio 1
	v_mfma_f32_16x16x32_bf16 v[62:65], v[170:173], v[186:189], v[62:65]
	v_mfma_f32_16x16x32_bf16 v[54:57], v[178:181], v[186:189], v[54:57]
	v_mfma_f32_16x16x32_bf16 v[46:49], v[170:173], v[194:197], v[46:49]
	v_mfma_f32_16x16x32_bf16 v[38:41], v[178:181], v[194:197], v[38:41]
	v_mfma_f32_16x16x32_bf16 v[30:33], v[170:173], v[206:209], v[30:33]
	v_mfma_f32_16x16x32_bf16 v[22:25], v[178:181], v[206:209], v[22:25]
	v_mfma_f32_16x16x32_bf16 v[14:17], v[170:173], v[226:229], v[14:17]
	v_mfma_f32_16x16x32_bf16 v[6:9], v[178:181], v[226:229], v[6:9]
	v_mfma_f32_16x16x32_bf16 v[62:65], v[174:177], v[190:193], v[62:65]
	v_mfma_f32_16x16x32_bf16 v[54:57], v[182:185], v[190:193], v[54:57]
	v_mfma_f32_16x16x32_bf16 v[46:49], v[174:177], v[202:205], v[46:49]
	v_mfma_f32_16x16x32_bf16 v[38:41], v[182:185], v[202:205], v[38:41]
	v_mfma_f32_16x16x32_bf16 v[30:33], v[174:177], v[210:213], v[30:33]
	v_mfma_f32_16x16x32_bf16 v[22:25], v[182:185], v[210:213], v[22:25]
	v_mfma_f32_16x16x32_bf16 v[14:17], v[174:177], v[230:233], v[14:17]
	v_mfma_f32_16x16x32_bf16 v[6:9], v[182:185], v[230:233], v[6:9]
	s_setprio 0
	s_nop 15
	s_setprio 0
	s_movk_i32 s7, 0x100
	v_cmp_gt_u32_e32 vcc, s7, v0
	s_barrier
	s_and_saveexec_b64 s[10:11], vcc
	s_cbranch_execz .LBB0_227
	s_barrier

; template <int EPI>
; DI void gemm_unit(const GemmP& g, int pm, int pn) {
;     ...
;     for (int ai = 0; ai < 2; ++ai)
; #pragma unroll
;       for (int m = 0; m < 4; ++m) {
;         const int row = row0 + ai * 128 + m * 16;
; #pragma unroll
;         for (int bj = 0; bj < 2; ++bj)
; #pragma unroll
;           for (int n = 0; n < 2; ++n) {
;             const int col = colb + bj * 128 + n * 16;
;             f32x4 v = acc[ai][bj][m][n];
;             if (EPI == EPI_BF16) {
;               if (col >= g.aux_n0) {
;                 const int c2 = col - g.aux_n0;
;                 if (c2 < g.aux_cnt) *(f32x4*)(g.aux + (size_t)row * 16 + c2) = v * g.aux_scale;
;               } else {
;                 if (g.colscale) v = v * *(const f32x4*)(g.colscale + col);
;                 uint2 o; o.x = pk2(v[0], v[1]); o.y = pk2(v[2], v[3]);
;                 *(uint2*)(g.Cb + (size_t)row * g.ldc + col) = o;
.LBB0_231:
	s_or_b64 exec, exec, s[8:9]
	v_or_b32_e32 v0, 0x80, v130
	v_cmp_gt_i32_e64 s[8:9], 2.0, v0
	s_and_saveexec_b64 s[10:11], s[8:9]
	s_cbranch_execz .LBB0_233
	v_cvt_pk_bf16_f32 v118, v122, v123
	v_cvt_pk_bf16_f32 v119, v124, v125
	v_lshl_add_u64 v[120:121], v[130:131], 1, v[134:135]
.LBB0_233:
	s_or_b64 exec, exec, s[10:11]
	v_or_b32_e32 v0, 0x90, v130
	v_cmp_gt_i32_e64 s[10:11], 2.0, v0
	s_and_saveexec_b64 s[18:19], s[10:11]
	s_cbranch_execz .LBB0_235
	v_cvt_pk_bf16_f32 v114, v114, v115
	v_cvt_pk_bf16_f32 v115, v116, v117
	v_lshl_add_u64 v[116:117], v[130:131], 1, v[134:135]
.LBB0_235:
	s_or_b64 exec, exec, s[18:19]
	v_or_b32_e32 v114, 16, v132
	v_ashrrev_i32_e32 v115, 31, v114
	v_lshlrev_b64 v[114:115], 10, v[114:115]
	v_lshl_add_u64 v[114:115], s[16:17], 0, v[114:115]
	s_and_saveexec_b64 s[18:19], vcc
	s_cbranch_execnz .LBB0_269
	s_or_b64 exec, exec, s[18:19]
	s_and_saveexec_b64 s[18:19], s[6:7]
	s_cbranch_execnz .LBB0_270

; template <int EPI>
; DI void gemm_unit(const GemmP& g, int pm, int pn) {
;     ...
;     for (int ai = 0; ai < 2; ++ai)
; #pragma unroll
;       for (int m = 0; m < 4; ++m) {
;         const int row = row0 + ai * 128 + m * 16;
; #pragma unroll
;         for (int bj = 0; bj < 2; ++bj)
; #pragma unroll
;           for (int n = 0; n < 2; ++n) {
;             const int col = colb + bj * 128 + n * 16;
;             f32x4 v = acc[ai][bj][m][n];
;             if (EPI == EPI_BF16) {
;               if (col >= g.aux_n0) {
;                 const int c2 = col - g.aux_n0;
;                 if (c2 < g.aux_cnt) *(f32x4*)(g.aux + (size_t)row * 16 + c2) = v * g.aux_scale;
;               } else {
;                 if (g.colscale) v = v * *(const f32x4*)(g.colscale + col);
;                 uint2 o; o.x = pk2(v[0], v[1]); o.y = pk2(v[2], v[3]);
;                 *(uint2*)(g.Cb + (size_t)row * g.ldc + col) = o;
.LBB0_239:
	v_cvt_pk_bf16_f32 v98, v98, v99
	v_cvt_pk_bf16_f32 v99, v100, v101
	v_lshl_add_u64 v[100:101], v[130:131], 1, v[114:115]
.LBB0_240:
	s_or_b64 exec, exec, s[18:19]
	v_or_b32_e32 v98, 32, v132
	v_ashrrev_i32_e32 v99, 31, v98
	v_lshlrev_b64 v[98:99], 10, v[98:99]
	v_lshl_add_u64 v[98:99], s[16:17], 0, v[98:99]
	s_and_saveexec_b64 s[18:19], vcc
	s_cbranch_execnz .LBB0_272
	s_or_b64 exec, exec, s[18:19]
	s_and_saveexec_b64 s[18:19], s[6:7]
	s_cbranch_execnz .LBB0_273

; template <int EPI>
; DI void gemm_unit(const GemmP& g, int pm, int pn) {
;     ...
;     for (int ai = 0; ai < 2; ++ai)
; #pragma unroll
;       for (int m = 0; m < 4; ++m) {
;         const int row = row0 + ai * 128 + m * 16;
; #pragma unroll
;         for (int bj = 0; bj < 2; ++bj)
; #pragma unroll
;           for (int n = 0; n < 2; ++n) {
;             const int col = colb + bj * 128 + n * 16;
;             f32x4 v = acc[ai][bj][m][n];
;             if (EPI == EPI_BF16) {
;               if (col >= g.aux_n0) {
;                 const int c2 = col - g.aux_n0;
;                 if (c2 < g.aux_cnt) *(f32x4*)(g.aux + (size_t)row * 16 + c2) = v * g.aux_scale;
;               } else {
;                 if (g.colscale) v = v * *(const f32x4*)(g.colscale + col);
;                 uint2 o; o.x = pk2(v[0], v[1]); o.y = pk2(v[2], v[3]);
;                 *(uint2*)(g.Cb + (size_t)row * g.ldc + col) = o;
.LBB0_244:
	v_cvt_pk_bf16_f32 v82, v82, v83
	v_cvt_pk_bf16_f32 v83, v84, v85
	v_lshl_add_u64 v[84:85], v[130:131], 1, v[98:99]
.LBB0_245:
	s_or_b64 exec, exec, s[18:19]
	v_or_b32_e32 v82, 48, v132
	v_ashrrev_i32_e32 v83, 31, v82
	v_lshlrev_b64 v[82:83], 10, v[82:83]
	v_lshl_add_u64 v[82:83], s[16:17], 0, v[82:83]
	s_and_saveexec_b64 s[18:19], vcc
	s_cbranch_execnz .LBB0_275
	s_or_b64 exec, exec, s[18:19]
	s_and_saveexec_b64 s[18:19], s[6:7]
	s_cbranch_execnz .LBB0_276

; template <int EPI>
; DI void gemm_unit(const GemmP& g, int pm, int pn) {
;     ...
;     for (int ai = 0; ai < 2; ++ai)
; #pragma unroll
;       for (int m = 0; m < 4; ++m) {
;         const int row = row0 + ai * 128 + m * 16;
; #pragma unroll
;         for (int bj = 0; bj < 2; ++bj)
; #pragma unroll
;           for (int n = 0; n < 2; ++n) {
;             const int col = colb + bj * 128 + n * 16;
;             f32x4 v = acc[ai][bj][m][n];
;             if (EPI == EPI_BF16) {
;               if (col >= g.aux_n0) {
;                 const int c2 = col - g.aux_n0;
;                 if (c2 < g.aux_cnt) *(f32x4*)(g.aux + (size_t)row * 16 + c2) = v * g.aux_scale;
;               } else {
;                 if (g.colscale) v = v * *(const f32x4*)(g.colscale + col);
;                 uint2 o; o.x = pk2(v[0], v[1]); o.y = pk2(v[2], v[3]);
;                 *(uint2*)(g.Cb + (size_t)row * g.ldc + col) = o;
.LBB0_249:
	v_cvt_pk_bf16_f32 v66, v66, v67
	v_cvt_pk_bf16_f32 v67, v68, v69
	v_lshl_add_u64 v[68:69], v[130:131], 1, v[82:83]
.LBB0_250:
	s_or_b64 exec, exec, s[18:19]
	v_add_u32_e32 v66, 0x80, v132
	v_ashrrev_i32_e32 v67, 31, v66
	v_lshlrev_b64 v[66:67], 10, v[66:67]
	v_lshl_add_u64 v[66:67], s[16:17], 0, v[66:67]
	s_and_saveexec_b64 s[18:19], vcc
	s_cbranch_execnz .LBB0_278
	s_or_b64 exec, exec, s[18:19]
	s_and_saveexec_b64 s[18:19], s[6:7]
	s_cbranch_execnz .LBB0_279

; template <int EPI>
; DI void gemm_unit(const GemmP& g, int pm, int pn) {
;     ...
;     for (int ai = 0; ai < 2; ++ai)
; #pragma unroll
;       for (int m = 0; m < 4; ++m) {
;         const int row = row0 + ai * 128 + m * 16;
; #pragma unroll
;         for (int bj = 0; bj < 2; ++bj)
; #pragma unroll
;           for (int n = 0; n < 2; ++n) {
;             const int col = colb + bj * 128 + n * 16;
;             f32x4 v = acc[ai][bj][m][n];
;             if (EPI == EPI_BF16) {
;               if (col >= g.aux_n0) {
;                 const int c2 = col - g.aux_n0;
;                 if (c2 < g.aux_cnt) *(f32x4*)(g.aux + (size_t)row * 16 + c2) = v * g.aux_scale;
;               } else {
;                 if (g.colscale) v = v * *(const f32x4*)(g.colscale + col);
;                 uint2 o; o.x = pk2(v[0], v[1]); o.y = pk2(v[2], v[3]);
;                 *(uint2*)(g.Cb + (size_t)row * g.ldc + col) = o;
.LBB0_254:
	v_cvt_pk_bf16_f32 v50, v50, v51
	v_cvt_pk_bf16_f32 v51, v52, v53
	v_lshl_add_u64 v[52:53], v[130:131], 1, v[66:67]
.LBB0_255:
	s_or_b64 exec, exec, s[18:19]
	v_add_u32_e32 v50, 0x90, v132
	v_ashrrev_i32_e32 v51, 31, v50
	v_lshlrev_b64 v[50:51], 10, v[50:51]
	v_lshl_add_u64 v[50:51], s[16:17], 0, v[50:51]
	s_and_saveexec_b64 s[18:19], vcc
	s_cbranch_execnz .LBB0_281
	s_or_b64 exec, exec, s[18:19]
	s_and_saveexec_b64 s[18:19], s[6:7]
	s_cbranch_execnz .LBB0_282

; template <int EPI>
; DI void gemm_unit(const GemmP& g, int pm, int pn) {
;     ...
;     for (int ai = 0; ai < 2; ++ai)
; #pragma unroll
;       for (int m = 0; m < 4; ++m) {
;         const int row = row0 + ai * 128 + m * 16;
; #pragma unroll
;         for (int bj = 0; bj < 2; ++bj)
; #pragma unroll
;           for (int n = 0; n < 2; ++n) {
;             const int col = colb + bj * 128 + n * 16;
;             f32x4 v = acc[ai][bj][m][n];
;             if (EPI == EPI_BF16) {
;               if (col >= g.aux_n0) {
;                 const int c2 = col - g.aux_n0;
;                 if (c2 < g.aux_cnt) *(f32x4*)(g.aux + (size_t)row * 16 + c2) = v * g.aux_scale;
;               } else {
;                 if (g.colscale) v = v * *(const f32x4*)(g.colscale + col);
;                 uint2 o; o.x = pk2(v[0], v[1]); o.y = pk2(v[2], v[3]);
;                 *(uint2*)(g.Cb + (size_t)row * g.ldc + col) = o;
.LBB0_259:
	v_cvt_pk_bf16_f32 v34, v34, v35
	v_cvt_pk_bf16_f32 v35, v36, v37
	v_lshl_add_u64 v[36:37], v[130:131], 1, v[50:51]
.LBB0_260:
	s_or_b64 exec, exec, s[18:19]
	v_add_u32_e32 v34, 0xa0, v132
	v_ashrrev_i32_e32 v35, 31, v34
	v_lshlrev_b64 v[34:35], 10, v[34:35]
	v_lshl_add_u64 v[34:35], s[16:17], 0, v[34:35]
	s_and_saveexec_b64 s[18:19], vcc
	s_cbranch_execnz .LBB0_284
	s_or_b64 exec, exec, s[18:19]
	s_and_saveexec_b64 s[18:19], s[6:7]
	s_cbranch_execnz .LBB0_285

; template <int EPI>
; DI void gemm_unit(const GemmP& g, int pm, int pn) {
;     ...
;     for (int ai = 0; ai < 2; ++ai)
; #pragma unroll
;       for (int m = 0; m < 4; ++m) {
;         const int row = row0 + ai * 128 + m * 16;
; #pragma unroll
;         for (int bj = 0; bj < 2; ++bj)
; #pragma unroll
;           for (int n = 0; n < 2; ++n) {
;             const int col = colb + bj * 128 + n * 16;
;             f32x4 v = acc[ai][bj][m][n];
;             if (EPI == EPI_BF16) {
;               if (col >= g.aux_n0) {
;                 const int c2 = col - g.aux_n0;
;                 if (c2 < g.aux_cnt) *(f32x4*)(g.aux + (size_t)row * 16 + c2) = v * g.aux_scale;
;               } else {
;                 if (g.colscale) v = v * *(const f32x4*)(g.colscale + col);
;                 uint2 o; o.x = pk2(v[0], v[1]); o.y = pk2(v[2], v[3]);
;                 *(uint2*)(g.Cb + (size_t)row * g.ldc + col) = o;
.LBB0_264:
	v_cvt_pk_bf16_f32 v18, v18, v19
	v_cvt_pk_bf16_f32 v19, v20, v21
	v_lshl_add_u64 v[20:21], v[130:131], 1, v[34:35]
.LBB0_265:
	s_or_b64 exec, exec, s[18:19]
	v_add_u32_e32 v18, 0xb0, v132
	v_ashrrev_i32_e32 v19, 31, v18
	v_lshlrev_b64 v[18:19], 10, v[18:19]
	v_lshl_add_u64 v[18:19], s[16:17], 0, v[18:19]
	s_and_saveexec_b64 s[18:19], vcc
	s_cbranch_execnz .LBB0_287
	s_or_b64 exec, exec, s[18:19]
	s_and_saveexec_b64 s[18:19], s[6:7]
	s_cbranch_execnz .LBB0_288

; template <int EPI>
; DI void gemm_unit(const GemmP& g, int pm, int pn) {
;     ...
;     for (int ai = 0; ai < 2; ++ai)
; #pragma unroll
;       for (int m = 0; m < 4; ++m) {
;         const int row = row0 + ai * 128 + m * 16;
; #pragma unroll
;         for (int bj = 0; bj < 2; ++bj)
; #pragma unroll
;           for (int n = 0; n < 2; ++n) {
;             const int col = colb + bj * 128 + n * 16;
;             f32x4 v = acc[ai][bj][m][n];
;             if (EPI == EPI_BF16) {
;               if (col >= g.aux_n0) {
;                 const int c2 = col - g.aux_n0;
;                 if (c2 < g.aux_cnt) *(f32x4*)(g.aux + (size_t)row * 16 + c2) = v * g.aux_scale;
;               } else {
;                 if (g.colscale) v = v * *(const f32x4*)(g.colscale + col);
;                 uint2 o; o.x = pk2(v[0], v[1]); o.y = pk2(v[2], v[3]);
;                 *(uint2*)(g.Cb + (size_t)row * g.ldc + col) = o;
.LBB0_271:
	v_cvt_pk_bf16_f32 v102, v106, v107
	v_cvt_pk_bf16_f32 v103, v108, v109
	v_lshl_add_u64 v[104:105], v[130:131], 1, v[114:115]
	s_or_b64 exec, exec, s[18:19]
	s_and_saveexec_b64 s[18:19], s[10:11]
	s_cbranch_execnz .LBB0_239
	s_branch .LBB0_240

; template <int EPI>
; DI void gemm_unit(const GemmP& g, int pm, int pn) {
;     ...
;     for (int ai = 0; ai < 2; ++ai)
; #pragma unroll
;       for (int m = 0; m < 4; ++m) {
;         const int row = row0 + ai * 128 + m * 16;
; #pragma unroll
;         for (int bj = 0; bj < 2; ++bj)
; #pragma unroll
;           for (int n = 0; n < 2; ++n) {
;             const int col = colb + bj * 128 + n * 16;
;             f32x4 v = acc[ai][bj][m][n];
;             if (EPI == EPI_BF16) {
;               if (col >= g.aux_n0) {
;                 const int c2 = col - g.aux_n0;
;                 if (c2 < g.aux_cnt) *(f32x4*)(g.aux + (size_t)row * 16 + c2) = v * g.aux_scale;
;               } else {
;                 if (g.colscale) v = v * *(const f32x4*)(g.colscale + col);
;                 uint2 o; o.x = pk2(v[0], v[1]); o.y = pk2(v[2], v[3]);
;                 *(uint2*)(g.Cb + (size_t)row * g.ldc + col) = o;
.LBB0_274:
	v_cvt_pk_bf16_f32 v86, v90, v91
	v_cvt_pk_bf16_f32 v87, v92, v93
	v_lshl_add_u64 v[88:89], v[130:131], 1, v[98:99]
	s_or_b64 exec, exec, s[18:19]
	s_and_saveexec_b64 s[18:19], s[10:11]
	s_cbranch_execnz .LBB0_244
	s_branch .LBB0_245

; template <int EPI>
; DI void gemm_unit(const GemmP& g, int pm, int pn) {
;     ...
;     for (int ai = 0; ai < 2; ++ai)
; #pragma unroll
;       for (int m = 0; m < 4; ++m) {
;         const int row = row0 + ai * 128 + m * 16;
; #pragma unroll
;         for (int bj = 0; bj < 2; ++bj)
; #pragma unroll
;           for (int n = 0; n < 2; ++n) {
;             const int col = colb + bj * 128 + n * 16;
;             f32x4 v = acc[ai][bj][m][n];
;             if (EPI == EPI_BF16) {
;               if (col >= g.aux_n0) {
;                 const int c2 = col - g.aux_n0;
;                 if (c2 < g.aux_cnt) *(f32x4*)(g.aux + (size_t)row * 16 + c2) = v * g.aux_scale;
;               } else {
;                 if (g.colscale) v = v * *(const f32x4*)(g.colscale + col);
;                 uint2 o; o.x = pk2(v[0], v[1]); o.y = pk2(v[2], v[3]);
;                 *(uint2*)(g.Cb + (size_t)row * g.ldc + col) = o;
.LBB0_277:
	v_cvt_pk_bf16_f32 v70, v74, v75
	v_cvt_pk_bf16_f32 v71, v76, v77
	v_lshl_add_u64 v[72:73], v[130:131], 1, v[82:83]
	s_or_b64 exec, exec, s[18:19]
	s_and_saveexec_b64 s[18:19], s[10:11]
	s_cbranch_execnz .LBB0_249
	s_branch .LBB0_250

; template <int EPI>
; DI void gemm_unit(const GemmP& g, int pm, int pn) {
;     ...
;     for (int ai = 0; ai < 2; ++ai)
; #pragma unroll
;       for (int m = 0; m < 4; ++m) {
;         const int row = row0 + ai * 128 + m * 16;
; #pragma unroll
;         for (int bj = 0; bj < 2; ++bj)
; #pragma unroll
;           for (int n = 0; n < 2; ++n) {
;             const int col = colb + bj * 128 + n * 16;
;             f32x4 v = acc[ai][bj][m][n];
;             if (EPI == EPI_BF16) {
;               if (col >= g.aux_n0) {
;                 const int c2 = col - g.aux_n0;
;                 if (c2 < g.aux_cnt) *(f32x4*)(g.aux + (size_t)row * 16 + c2) = v * g.aux_scale;
;               } else {
;                 if (g.colscale) v = v * *(const f32x4*)(g.colscale + col);
;                 uint2 o; o.x = pk2(v[0], v[1]); o.y = pk2(v[2], v[3]);
;                 *(uint2*)(g.Cb + (size_t)row * g.ldc + col) = o;
.LBB0_280:
	v_cvt_pk_bf16_f32 v54, v58, v59
	v_cvt_pk_bf16_f32 v55, v60, v61
	v_lshl_add_u64 v[56:57], v[130:131], 1, v[66:67]
	s_or_b64 exec, exec, s[18:19]
	s_and_saveexec_b64 s[18:19], s[10:11]
	s_cbranch_execnz .LBB0_254
	s_branch .LBB0_255

; template <int EPI>
; DI void gemm_unit(const GemmP& g, int pm, int pn) {
;     ...
;     for (int ai = 0; ai < 2; ++ai)
; #pragma unroll
;       for (int m = 0; m < 4; ++m) {
;         const int row = row0 + ai * 128 + m * 16;
; #pragma unroll
;         for (int bj = 0; bj < 2; ++bj)
; #pragma unroll
;           for (int n = 0; n < 2; ++n) {
;             const int col = colb + bj * 128 + n * 16;
;             f32x4 v = acc[ai][bj][m][n];
;             if (EPI == EPI_BF16) {
;               if (col >= g.aux_n0) {
;                 const int c2 = col - g.aux_n0;
;                 if (c2 < g.aux_cnt) *(f32x4*)(g.aux + (size_t)row * 16 + c2) = v * g.aux_scale;
;               } else {
;                 if (g.colscale) v = v * *(const f32x4*)(g.colscale + col);
;                 uint2 o; o.x = pk2(v[0], v[1]); o.y = pk2(v[2], v[3]);
;                 *(uint2*)(g.Cb + (size_t)row * g.ldc + col) = o;
.LBB0_283:
	v_cvt_pk_bf16_f32 v38, v42, v43
	v_cvt_pk_bf16_f32 v39, v44, v45
	v_lshl_add_u64 v[40:41], v[130:131], 1, v[50:51]
	s_or_b64 exec, exec, s[18:19]
	s_and_saveexec_b64 s[18:19], s[10:11]
	s_cbranch_execnz .LBB0_259
	s_branch .LBB0_260

; template <int EPI>
; DI void gemm_unit(const GemmP& g, int pm, int pn) {
;     ...
;     for (int ai = 0; ai < 2; ++ai)
; #pragma unroll
;       for (int m = 0; m < 4; ++m) {
;         const int row = row0 + ai * 128 + m * 16;
; #pragma unroll
;         for (int bj = 0; bj < 2; ++bj)
; #pragma unroll
;           for (int n = 0; n < 2; ++n) {
;             const int col = colb + bj * 128 + n * 16;
;             f32x4 v = acc[ai][bj][m][n];
;             if (EPI == EPI_BF16) {
;               if (col >= g.aux_n0) {
;                 const int c2 = col - g.aux_n0;
;                 if (c2 < g.aux_cnt) *(f32x4*)(g.aux + (size_t)row * 16 + c2) = v * g.aux_scale;
;               } else {
;                 if (g.colscale) v = v * *(const f32x4*)(g.colscale + col);
;                 uint2 o; o.x = pk2(v[0], v[1]); o.y = pk2(v[2], v[3]);
;                 *(uint2*)(g.Cb + (size_t)row * g.ldc + col) = o;
.LBB0_286:
	v_cvt_pk_bf16_f32 v22, v26, v27
	v_cvt_pk_bf16_f32 v23, v28, v29
	v_lshl_add_u64 v[24:25], v[130:131], 1, v[34:35]
	s_or_b64 exec, exec, s[18:19]
	s_and_saveexec_b64 s[18:19], s[10:11]
	s_cbranch_execnz .LBB0_264
	s_branch .LBB0_265

; template <int EPI>
; DI void gemm_unit(const GemmP& g, int pm, int pn) {
;     ...
;     for (int ai = 0; ai < 2; ++ai)
; #pragma unroll
;       for (int m = 0; m < 4; ++m) {
;         const int row = row0 + ai * 128 + m * 16;
; #pragma unroll
;         for (int bj = 0; bj < 2; ++bj)
; #pragma unroll
;           for (int n = 0; n < 2; ++n) {
;             const int col = colb + bj * 128 + n * 16;
;             f32x4 v = acc[ai][bj][m][n];
;             if (EPI == EPI_BF16) {
;               if (col >= g.aux_n0) {
;                 const int c2 = col - g.aux_n0;
;                 if (c2 < g.aux_cnt) *(f32x4*)(g.aux + (size_t)row * 16 + c2) = v * g.aux_scale;
;               } else {
;                 if (g.colscale) v = v * *(const f32x4*)(g.colscale + col);
;                 uint2 o; o.x = pk2(v[0], v[1]); o.y = pk2(v[2], v[3]);
;                 *(uint2*)(g.Cb + (size_t)row * g.ldc + col) = o;
.LBB0_289:
	v_cvt_pk_bf16_f32 v6, v10, v11
	v_cvt_pk_bf16_f32 v7, v12, v13
	v_lshl_add_u64 v[8:9], v[130:131], 1, v[18:19]
	s_or_b64 exec, exec, s[6:7]
	s_and_saveexec_b64 s[6:7], s[10:11]
	s_cbranch_execz .LBB0_216
.LBB0_290:
	v_cvt_pk_bf16_f32 v2, v2, v3
	v_cvt_pk_bf16_f32 v3, v4, v5
	v_lshl_add_u64 v[4:5], v[130:131], 1, v[18:19]
	s_branch .LBB0_216
